# LRU scan plane stores (HA: 35 MB per layer, consumed by fix-up on other XCDs) write-through (sc1): less dirty L2 to flush at the P2|P3 grid barrier
# speedup vs baseline: 1.0064x; 1.0032x over previous
.LBB0_320:
	s_lshl_b64 s[10:11], s[6:7], 10
	v_lshl_add_u64 v[114:115], v[126:127], 0, s[10:11]
	s_add_u32 s10, s10, 0x1000
	s_addc_u32 s11, s11, 0
	v_lshl_add_u64 v[116:117], v[126:127], 0, s[10:11]
	s_add_u32 s10, s10, 0x1000
	s_addc_u32 s11, s11, 0
	v_lshl_add_u64 v[118:119], v[126:127], 0, s[10:11]
	s_add_u32 s10, s10, 0x1000
	s_addc_u32 s11, s11, 0
	v_lshl_add_u64 v[120:121], v[126:127], 0, s[10:11]
	s_and_b64 s[10:11], s[56:57], exec
	s_cbranch_scc0 .Lscan_bwd
	ds_read_b32 v226, v132 offset:0
	ds_read_b32 v242, v132 offset:4352
	ds_read_b32 v227, v132 offset:272
	ds_read_b32 v243, v132 offset:4624
	ds_read_b32 v228, v132 offset:544
	ds_read_b32 v244, v132 offset:4896
	ds_read_b32 v229, v132 offset:816
	ds_read_b32 v245, v132 offset:5168
	ds_read_b32 v230, v132 offset:1088
	ds_read_b32 v246, v132 offset:5440
	ds_read_b32 v231, v132 offset:1360
	ds_read_b32 v133, v132 offset:5712
	ds_read_b32 v232, v132 offset:1632
	ds_read_b32 v134, v132 offset:5984
	ds_read_b32 v233, v132 offset:1904
	ds_read_b32 v135, v132 offset:6256
	s_waitcnt lgkmcnt(14)
	v_mul_f32_e32 v144, v130, v226
	v_fmac_f32_e32 v242, v129, v226
	v_cvt_pk_bf16_f32 v145, v242, v144
	global_store_dword v[114:115], v145, off sc1
	ds_read_b32 v234, v132 offset:2176
	ds_read_b32 v136, v132 offset:6528
	s_waitcnt lgkmcnt(14)
	v_mul_f32_e32 v130, v144, v227
	v_fmac_f32_e32 v243, v242, v227
	v_cvt_pk_bf16_f32 v146, v243, v130
	global_store_dword v[114:115], v146, off offset:1024 sc1
	ds_read_b32 v235, v132 offset:2448
	ds_read_b32 v137, v132 offset:6800
	s_waitcnt lgkmcnt(14)
	v_mul_f32_e32 v144, v130, v228
	v_fmac_f32_e32 v244, v243, v228
	v_cvt_pk_bf16_f32 v145, v244, v144
	global_store_dword v[114:115], v145, off offset:2048 sc1
	ds_read_b32 v236, v132 offset:2720
	ds_read_b32 v138, v132 offset:7072
	s_waitcnt lgkmcnt(14)
	v_mul_f32_e32 v130, v144, v229
	v_fmac_f32_e32 v245, v244, v229
	v_cvt_pk_bf16_f32 v146, v245, v130
	global_store_dword v[114:115], v146, off offset:3072 sc1
	ds_read_b32 v237, v132 offset:2992
	ds_read_b32 v139, v132 offset:7344
	s_waitcnt lgkmcnt(14)
	v_mul_f32_e32 v144, v130, v230
	v_fmac_f32_e32 v246, v245, v230
	v_cvt_pk_bf16_f32 v145, v246, v144
	global_store_dword v[116:117], v145, off sc1
	ds_read_b32 v238, v132 offset:3264
	ds_read_b32 v140, v132 offset:7616
	s_waitcnt lgkmcnt(14)
	v_mul_f32_e32 v130, v144, v231
	v_fmac_f32_e32 v133, v246, v231
	v_cvt_pk_bf16_f32 v146, v133, v130
	global_store_dword v[116:117], v146, off offset:1024 sc1
	ds_read_b32 v239, v132 offset:3536
	ds_read_b32 v141, v132 offset:7888
	s_waitcnt lgkmcnt(14)
	v_mul_f32_e32 v144, v130, v232
	v_fmac_f32_e32 v134, v133, v232
	v_cvt_pk_bf16_f32 v145, v134, v144
	global_store_dword v[116:117], v145, off offset:2048 sc1
	ds_read_b32 v240, v132 offset:3808
	ds_read_b32 v142, v132 offset:8160
	s_waitcnt lgkmcnt(14)
	v_mul_f32_e32 v130, v144, v233
	v_fmac_f32_e32 v135, v134, v233
	v_cvt_pk_bf16_f32 v146, v135, v130
	global_store_dword v[116:117], v146, off offset:3072 sc1
	ds_read_b32 v241, v132 offset:4080
	ds_read_b32 v143, v132 offset:8432
	s_waitcnt lgkmcnt(14)
	v_mul_f32_e32 v144, v130, v234
	v_fmac_f32_e32 v136, v135, v234
	v_cvt_pk_bf16_f32 v145, v136, v144
	global_store_dword v[118:119], v145, off sc1
	s_waitcnt lgkmcnt(12)
	v_mul_f32_e32 v130, v144, v235
	v_fmac_f32_e32 v137, v136, v235
	v_cvt_pk_bf16_f32 v146, v137, v130
	global_store_dword v[118:119], v146, off offset:1024 sc1
	s_waitcnt lgkmcnt(10)
	v_mul_f32_e32 v144, v130, v236
	v_fmac_f32_e32 v138, v137, v236
	v_cvt_pk_bf16_f32 v145, v138, v144
	global_store_dword v[118:119], v145, off offset:2048 sc1
	s_waitcnt lgkmcnt(8)
	v_mul_f32_e32 v130, v144, v237
	v_fmac_f32_e32 v139, v138, v237
	v_cvt_pk_bf16_f32 v146, v139, v130
	global_store_dword v[118:119], v146, off offset:3072 sc1
	s_waitcnt lgkmcnt(6)
	v_mul_f32_e32 v144, v130, v238
	v_fmac_f32_e32 v140, v139, v238
	v_cvt_pk_bf16_f32 v145, v140, v144
	global_store_dword v[120:121], v145, off sc1
	s_waitcnt lgkmcnt(4)
	v_mul_f32_e32 v130, v144, v239
	v_fmac_f32_e32 v141, v140, v239
	v_cvt_pk_bf16_f32 v146, v141, v130
	global_store_dword v[120:121], v146, off offset:1024 sc1
	s_waitcnt lgkmcnt(2)
	v_mul_f32_e32 v144, v130, v240
	v_fmac_f32_e32 v142, v141, v240
	v_cvt_pk_bf16_f32 v145, v142, v144
	global_store_dword v[120:121], v145, off offset:2048 sc1
	s_waitcnt lgkmcnt(0)
	v_mul_f32_e32 v130, v144, v241
	v_fmac_f32_e32 v143, v142, v241
	v_cvt_pk_bf16_f32 v146, v143, v130
	global_store_dword v[120:121], v146, off offset:3072 sc1
	v_mov_b32_e32 v129, v143
	s_branch .Lscan_done
.Lscan_bwd:
	ds_read_b32 v241, v132 offset:4080
	ds_read_b32 v143, v132 offset:8432
	ds_read_b32 v240, v132 offset:3808
	ds_read_b32 v142, v132 offset:8160
	ds_read_b32 v239, v132 offset:3536
	ds_read_b32 v141, v132 offset:7888
	ds_read_b32 v238, v132 offset:3264
	ds_read_b32 v140, v132 offset:7616
	ds_read_b32 v237, v132 offset:2992
	ds_read_b32 v139, v132 offset:7344
	ds_read_b32 v236, v132 offset:2720
	ds_read_b32 v138, v132 offset:7072
	ds_read_b32 v235, v132 offset:2448
	ds_read_b32 v137, v132 offset:6800
	ds_read_b32 v234, v132 offset:2176
	ds_read_b32 v136, v132 offset:6528
	s_waitcnt lgkmcnt(14)
	v_mul_f32_e32 v144, v130, v241
	v_fmac_f32_e32 v143, v129, v241
	v_cvt_pk_bf16_f32 v145, v143, v144
	global_store_dword v[120:121], v145, off offset:3072 sc1
	ds_read_b32 v233, v132 offset:1904
	ds_read_b32 v135, v132 offset:6256
	s_waitcnt lgkmcnt(14)
	v_mul_f32_e32 v130, v144, v240
	v_fmac_f32_e32 v142, v143, v240
	v_cvt_pk_bf16_f32 v146, v142, v130
	global_store_dword v[120:121], v146, off offset:2048 sc1
	ds_read_b32 v232, v132 offset:1632
	ds_read_b32 v134, v132 offset:5984
	s_waitcnt lgkmcnt(14)
	v_mul_f32_e32 v144, v130, v239
	v_fmac_f32_e32 v141, v142, v239
	v_cvt_pk_bf16_f32 v145, v141, v144
	global_store_dword v[120:121], v145, off offset:1024 sc1
	ds_read_b32 v231, v132 offset:1360
	ds_read_b32 v133, v132 offset:5712
	s_waitcnt lgkmcnt(14)
	v_mul_f32_e32 v130, v144, v238
	v_fmac_f32_e32 v140, v141, v238
	v_cvt_pk_bf16_f32 v146, v140, v130
	global_store_dword v[120:121], v146, off sc1
	ds_read_b32 v230, v132 offset:1088
	ds_read_b32 v246, v132 offset:5440
	s_waitcnt lgkmcnt(14)
	v_mul_f32_e32 v144, v130, v237
	v_fmac_f32_e32 v139, v140, v237
	v_cvt_pk_bf16_f32 v145, v139, v144
	global_store_dword v[118:119], v145, off offset:3072 sc1
	ds_read_b32 v229, v132 offset:816
	ds_read_b32 v245, v132 offset:5168
	s_waitcnt lgkmcnt(14)
	v_mul_f32_e32 v130, v144, v236
	v_fmac_f32_e32 v138, v139, v236
	v_cvt_pk_bf16_f32 v146, v138, v130
	global_store_dword v[118:119], v146, off offset:2048 sc1
	ds_read_b32 v228, v132 offset:544
	ds_read_b32 v244, v132 offset:4896
	s_waitcnt lgkmcnt(14)
	v_mul_f32_e32 v144, v130, v235
	v_fmac_f32_e32 v137, v138, v235
	v_cvt_pk_bf16_f32 v145, v137, v144
	global_store_dword v[118:119], v145, off offset:1024 sc1
	ds_read_b32 v227, v132 offset:272
	ds_read_b32 v243, v132 offset:4624
	s_waitcnt lgkmcnt(14)
	v_mul_f32_e32 v130, v144, v234
	v_fmac_f32_e32 v136, v137, v234
	v_cvt_pk_bf16_f32 v146, v136, v130
	global_store_dword v[118:119], v146, off sc1
	ds_read_b32 v226, v132 offset:0
	ds_read_b32 v242, v132 offset:4352
	s_waitcnt lgkmcnt(14)
	v_mul_f32_e32 v144, v130, v233
	v_fmac_f32_e32 v135, v136, v233
	v_cvt_pk_bf16_f32 v145, v135, v144
	global_store_dword v[116:117], v145, off offset:3072 sc1
	s_waitcnt lgkmcnt(12)
	v_mul_f32_e32 v130, v144, v232
	v_fmac_f32_e32 v134, v135, v232
	v_cvt_pk_bf16_f32 v146, v134, v130
	global_store_dword v[116:117], v146, off offset:2048 sc1
	s_waitcnt lgkmcnt(10)
	v_mul_f32_e32 v144, v130, v231
	v_fmac_f32_e32 v133, v134, v231
	v_cvt_pk_bf16_f32 v145, v133, v144
	global_store_dword v[116:117], v145, off offset:1024 sc1
	s_waitcnt lgkmcnt(8)
	v_mul_f32_e32 v130, v144, v230
	v_fmac_f32_e32 v246, v133, v230
	v_cvt_pk_bf16_f32 v146, v246, v130
	global_store_dword v[116:117], v146, off sc1
	s_waitcnt lgkmcnt(6)
	v_mul_f32_e32 v144, v130, v229
	v_fmac_f32_e32 v245, v246, v229
	v_cvt_pk_bf16_f32 v145, v245, v144
	global_store_dword v[114:115], v145, off offset:3072 sc1
	s_waitcnt lgkmcnt(4)
	v_mul_f32_e32 v130, v144, v228
	v_fmac_f32_e32 v244, v245, v228
	v_cvt_pk_bf16_f32 v146, v244, v130
	global_store_dword v[114:115], v146, off offset:2048 sc1
	s_waitcnt lgkmcnt(2)
	v_mul_f32_e32 v144, v130, v227
	v_fmac_f32_e32 v243, v244, v227
	v_cvt_pk_bf16_f32 v145, v243, v144
	global_store_dword v[114:115], v145, off offset:1024 sc1
	s_waitcnt lgkmcnt(0)
	v_mul_f32_e32 v130, v144, v226
	v_fmac_f32_e32 v242, v243, v226
	v_cvt_pk_bf16_f32 v146, v242, v130
	global_store_dword v[114:115], v146, off sc1
	v_mov_b32_e32 v129, v242
